# final RMSNorm weights hoisted out of the row loop; phase_u (fp16 residual) requests all modulation fragments with the row - stores no longer drained per 8-column group
# speedup vs baseline: 1.0636x; 1.0021x over previous
; __device__ __forceinline__ void phase_u_h(const Params& p, int l, int wave, int lane, int G) {
;     half_t* U = (half_t*)(p.ws + WS_U); const float* mod = (const float*)(p.ws + WS_MOD); const half_t* Hh = (const half_t*)(p.ws + WS_H);
;     const int gw = blockIdx.x * 8 + wave, NGW = G * 8;
;     for (int row = gw; row < NTOK; row += NGW) {
;         f32x4 v[8];
;         const float ss = wave_sum(load_hrow(Hh + (size_t)row * DM, lane, v), lane);
;         const float rinv = 1.0f / sqrtf(ss * (1.f / DM) + EPS);
;         const float* mb = mod + (size_t)(l * 2 + (row >> 12)) * 6144;
; #pragma unroll
;         for (int j = 0; j < 4; ++j) { const int col = 8 * lane + 512 * j;
;             h8 o;
; #pragma unroll
;             for (int hh = 0; hh < 2; ++hh) { const int c = col + 4 * hh;
;                 const f32x4 nw = *(const f32x4*)(p.norm_w + l * DM + c), sh = *(const f32x4*)(mb + c), sc = *(const f32x4*)(mb + 2048 + c);
;                 const f32x4 uu = (v[2 * j + hh] * rinv) * nw * (sc + 1.f) + sh;
;                 o[4 * hh] = op16(uu[0], INPROJ_BF16); o[4 * hh + 1] = op16(uu[1], INPROJ_BF16); o[4 * hh + 2] = op16(uu[2], INPROJ_BF16); o[4 * hh + 3] = op16(uu[3], INPROJ_BF16); }
;             *(h8*)(U + (size_t)row * DM + col) = o; }
.LBB0_232:
	global_load_dwordx4 v[4:7], v[12:13], off
	global_load_dwordx4 v[14:17], v[12:13], off offset:1024
	global_load_dwordx4 v[28:31], v[12:13], off offset:2048
	global_load_dwordx4 v[32:35], v[12:13], off offset:3072
	s_ashr_i32 s6, s1, 12
	s_mov_b32 s7, 0xe9000000
	s_add_i32 s6, s6, s12
	v_add_co_u32_e32 v60, vcc, s7, v12
	s_mul_hi_i32 s7, s6, 0x6000
	s_mulk_i32 s6, 0x6000
	s_add_u32 s8, s62, s6
	s_addc_u32 s9, s63, s7
	s_add_u32 s10, s8, 0x2000
	s_addc_u32 s11, s9, 0
	global_load_dwordx4 v[36:39], v[0:1], off offset:16
	global_load_dwordx4 v[40:43], v[0:1], off
	global_load_dwordx4 v[44:47], v2, s[8:9] offset:16
	global_load_dwordx4 v[48:51], v2, s[8:9]
	global_load_dwordx4 v[52:55], v2, s[10:11]
	global_load_dwordx4 v[56:59], v2, s[10:11] offset:16
	global_load_dwordx4 v[192:195], v[0:1], off offset:2048
	global_load_dwordx4 v[196:199], v25, s[10:11]
	global_load_dwordx4 v[200:203], v[0:1], off offset:2064
	global_load_dwordx4 v[204:207], v25, s[10:11] offset:16
	global_load_dwordx4 v[208:211], v2, s[8:9] offset:2048
	global_load_dwordx4 v[212:215], v2, s[8:9] offset:2064
	global_load_dwordx4 v[216:219], v[8:9], off
	global_load_dwordx4 v[220:223], v26, s[10:11]
	global_load_dwordx4 v[224:227], v[8:9], off offset:16
	global_load_dwordx4 v[228:231], v26, s[10:11] offset:16
	global_load_dwordx4 v[232:235], v26, s[8:9]
	global_load_dwordx4 v[236:239], v26, s[8:9] offset:16
	global_load_dwordx4 v[240:243], v[10:11], off
	global_load_dwordx4 v[244:247], v27, s[10:11]
	global_load_dwordx4 v[108:111], v[10:11], off offset:16
	global_load_dwordx4 v[112:115], v27, s[10:11] offset:16
	global_load_dwordx4 v[116:119], v27, s[8:9]
	global_load_dwordx4 v[120:123], v27, s[8:9] offset:16
	v_addc_co_u32_e32 v61, vcc, -1, v13, vcc
	s_add_i32 s1, s1, s68
	s_cmpk_lt_i32 s1, 0x2000
	s_waitcnt vmcnt(27)
	v_cvt_f32_f16_sdwa v63, v4 dst_sel:DWORD dst_unused:UNUSED_PAD src0_sel:WORD_1
	v_cvt_f32_f16_sdwa v65, v5 dst_sel:DWORD dst_unused:UNUSED_PAD src0_sel:WORD_1
	v_cvt_f32_f16_sdwa v67, v6 dst_sel:DWORD dst_unused:UNUSED_PAD src0_sel:WORD_1
	v_cvt_f32_f16_sdwa v69, v7 dst_sel:DWORD dst_unused:UNUSED_PAD src0_sel:WORD_1
	v_cvt_f32_f16_e32 v62, v4
	v_cvt_f32_f16_e32 v64, v5
	v_cvt_f32_f16_e32 v66, v6
	v_cvt_f32_f16_e32 v68, v7
	s_waitcnt vmcnt(26)
	v_cvt_f32_f16_sdwa v75, v15 dst_sel:DWORD dst_unused:UNUSED_PAD src0_sel:WORD_1
	v_cvt_f32_f16_sdwa v74, v14 dst_sel:DWORD dst_unused:UNUSED_PAD src0_sel:WORD_1
	v_cvt_f32_f16_e32 v70, v16
	v_cvt_f32_f16_e32 v73, v15
	v_cvt_f32_f16_e32 v72, v14
	v_cvt_f32_f16_e32 v76, v17
	v_cvt_f32_f16_sdwa v71, v16 dst_sel:DWORD dst_unused:UNUSED_PAD src0_sel:WORD_1
	v_cvt_f32_f16_sdwa v77, v17 dst_sel:DWORD dst_unused:UNUSED_PAD src0_sel:WORD_1
	s_waitcnt vmcnt(25)
	v_cvt_f32_f16_sdwa v79, v28 dst_sel:DWORD dst_unused:UNUSED_PAD src0_sel:WORD_1
	v_cvt_f32_f16_e32 v78, v28
	v_cvt_f32_f16_sdwa v81, v29 dst_sel:DWORD dst_unused:UNUSED_PAD src0_sel:WORD_1
	v_cvt_f32_f16_e32 v80, v29
	v_cvt_f32_f16_e32 v83, v31
	v_cvt_f32_f16_e32 v82, v30
	v_cvt_f32_f16_sdwa v85, v31 dst_sel:DWORD dst_unused:UNUSED_PAD src0_sel:WORD_1
	v_cvt_f32_f16_sdwa v84, v30 dst_sel:DWORD dst_unused:UNUSED_PAD src0_sel:WORD_1
	s_waitcnt vmcnt(24)
	v_cvt_f32_f16_sdwa v5, v34 dst_sel:DWORD dst_unused:UNUSED_PAD src0_sel:WORD_1
	v_cvt_f32_f16_e32 v4, v34
	v_cvt_f32_f16_sdwa v15, v35 dst_sel:DWORD dst_unused:UNUSED_PAD src0_sel:WORD_1
	v_cvt_f32_f16_e32 v14, v35
	v_mov_b32_e32 v30, v67
	v_mov_b32_e32 v31, v63
	v_mov_b32_e32 v34, v69
	v_mov_b32_e32 v35, v65
	v_cvt_f32_f16_sdwa v7, v32 dst_sel:DWORD dst_unused:UNUSED_PAD src0_sel:WORD_1
	v_cvt_f32_f16_e32 v6, v32
	v_cvt_f32_f16_sdwa v17, v33 dst_sel:DWORD dst_unused:UNUSED_PAD src0_sel:WORD_1
	v_cvt_f32_f16_e32 v16, v33
	v_mov_b32_e32 v28, v66
	v_mov_b32_e32 v29, v62
	v_mov_b32_e32 v32, v68
	v_mov_b32_e32 v33, v64
	v_pk_mul_f32 v[30:31], v[30:31], v[30:31]
	v_pk_mul_f32 v[34:35], v[34:35], v[34:35]
	v_pk_mul_f32 v[86:87], v[74:75], v[74:75]
	v_pk_fma_f32 v[28:29], v[28:29], v[28:29], v[30:31]
	v_pk_fma_f32 v[30:31], v[32:33], v[32:33], v[34:35]
	v_mul_f32_e32 v88, v76, v76
	v_mul_f32_e32 v94, v70, v70
	v_pk_fma_f32 v[86:87], v[72:73], v[72:73], v[86:87]
	v_pk_add_f32 v[28:29], v[28:29], v[30:31]
	v_pk_mul_f32 v[90:91], v[78:79], v[78:79]
	v_pk_mul_f32 v[92:93], v[80:81], v[80:81]
	v_pk_fma_f32 v[88:89], v[76:77], v[76:77], v[88:89] op_sel_hi:[1,1,0]
	v_pk_fma_f32 v[94:95], v[70:71], v[70:71], v[94:95] op_sel_hi:[1,1,0]
	v_pk_add_f32 v[32:33], v[86:87], v[86:87] op_sel_hi:[0,1]
	v_pk_add_f32 v[28:29], v[28:29], v[28:29] op_sel_hi:[0,1]
	v_mov_b32_e32 v94, v90
	v_mov_b32_e32 v88, v91
	v_mov_b32_e32 v32, v93
	v_mov_b32_e32 v28, v92
	v_pk_mul_f32 v[96:97], v[84:85], v[84:85]
	v_pk_add_f32 v[30:31], v[94:95], v[88:89]
	v_pk_add_f32 v[28:29], v[28:29], v[32:33]
	v_mul_f32_e32 v98, v16, v16
	v_mul_f32_e32 v104, v6, v6
	v_pk_fma_f32 v[96:97], v[82:83], v[82:83], v[96:97]
	v_pk_add_f32 v[28:29], v[30:31], v[28:29]
	v_pk_mul_f32 v[100:101], v[4:5], v[4:5]
	v_pk_mul_f32 v[102:103], v[14:15], v[14:15]
	v_pk_fma_f32 v[98:99], v[16:17], v[16:17], v[98:99] op_sel_hi:[1,1,0]
	v_pk_fma_f32 v[104:105], v[6:7], v[6:7], v[104:105] op_sel_hi:[1,1,0]
	v_pk_add_f32 v[34:35], v[96:97], v[96:97] op_sel_hi:[0,1]
	v_pk_add_f32 v[28:29], v[28:29], v[28:29] op_sel_hi:[0,1]
	v_mov_b32_e32 v104, v100
	v_mov_b32_e32 v98, v101
	v_mov_b32_e32 v34, v102
	v_mov_b32_e32 v28, v103
	v_pk_add_f32 v[86:87], v[104:105], v[98:99]
	v_pk_add_f32 v[28:29], v[34:35], v[28:29]
	s_waitcnt vmcnt(19)
	v_pk_add_f32 v[54:55], v[54:55], 1.0 op_sel_hi:[1,0]
	v_pk_add_f32 v[28:29], v[86:87], v[28:29]
	v_pk_add_f32 v[52:53], v[52:53], 1.0 op_sel_hi:[1,0]
	v_add_f32_e32 v28, v28, v29
	ds_bpermute_b32 v29, v19, v28
	s_waitcnt vmcnt(18)
; __device__ __forceinline__ void phase_u_h(const Params& p, int l, int wave, int lane, int G) {
;     ...
;         const float ss = wave_sum(load_hrow(Hh + (size_t)row * DM, lane, v), lane);
;         const float rinv = 1.0f / sqrtf(ss * (1.f / DM) + EPS);
;         const float* mb = mod + (size_t)(l * 2 + (row >> 12)) * 6144;
; #pragma unroll
;         for (int j = 0; j < 4; ++j) { const int col = 8 * lane + 512 * j;
;             h8 o;
; #pragma unroll
;             for (int hh = 0; hh < 2; ++hh) { const int c = col + 4 * hh;
;                 const f32x4 nw = *(const f32x4*)(p.norm_w + l * DM + c), sh = *(const f32x4*)(mb + c), sc = *(const f32x4*)(mb + 2048 + c);
;                 const f32x4 uu = (v[2 * j + hh] * rinv) * nw * (sc + 1.f) + sh;
;                 o[4 * hh] = op16(uu[0], INPROJ_BF16); o[4 * hh + 1] = op16(uu[1], INPROJ_BF16); o[4 * hh + 2] = op16(uu[2], INPROJ_BF16); o[4 * hh + 3] = op16(uu[3], INPROJ_BF16); }
;             *(h8*)(U + (size_t)row * DM + col) = o; }
	v_pk_add_f32 v[58:59], v[58:59], 1.0 op_sel_hi:[1,0]
	v_pk_add_f32 v[56:57], v[56:57], 1.0 op_sel_hi:[1,0]
	s_waitcnt lgkmcnt(0)
	v_add_f32_e32 v28, v28, v29
	ds_bpermute_b32 v29, v20, v28
	s_waitcnt lgkmcnt(0)
	v_add_f32_e32 v28, v28, v29
	ds_bpermute_b32 v29, v21, v28
	s_waitcnt lgkmcnt(0)
	v_add_f32_e32 v28, v28, v29
	ds_bpermute_b32 v29, v22, v28
	s_waitcnt lgkmcnt(0)
	v_add_f32_e32 v28, v28, v29
	ds_bpermute_b32 v29, v23, v28
	s_waitcnt lgkmcnt(0)
	v_add_f32_e32 v28, v28, v29
	ds_bpermute_b32 v29, v24, v28
	s_waitcnt lgkmcnt(0)
	v_add_f32_e32 v28, v28, v29
	v_fmamk_f32 v28, v28, 0x3a000000, v181
	v_mul_f32_e32 v29, 0x4f800000, v28
	v_cmp_gt_f32_e32 vcc, s22, v28
	s_nop 1
	v_cndmask_b32_e32 v28, v28, v29, vcc
	v_sqrt_f32_e32 v29, v28
	s_nop 0
	v_add_u32_e32 v30, -1, v29
	v_add_u32_e32 v31, 1, v29
	v_fma_f32 v32, -v30, v29, v28
	v_fma_f32 v33, -v31, v29, v28
	v_cmp_ge_f32_e64 s[6:7], 0, v32
	s_nop 1
	v_cndmask_b32_e64 v29, v29, v30, s[6:7]
	v_cmp_lt_f32_e64 s[6:7], 0, v33
	s_nop 1
	v_cndmask_b32_e64 v29, v29, v31, s[6:7]
	v_mul_f32_e32 v30, 0x37800000, v29
	v_cndmask_b32_e32 v29, v29, v30, vcc
	v_cmp_class_f32_e32 vcc, v28, v182
	s_nop 1
	v_cndmask_b32_e32 v28, v29, v28, vcc
	v_div_scale_f32 v29, s[6:7], v28, v28, 1.0
	v_rcp_f32_e32 v31, v29
	v_div_scale_f32 v30, vcc, 1.0, v28, 1.0
	s_mov_b32 s6, 0xe9001000
	v_fma_f32 v32, -v29, v31, 1.0
	v_fmac_f32_e32 v31, v32, v31
	v_mul_f32_e32 v32, v30, v31
	v_fma_f32 v33, -v29, v32, v30
	v_fmac_f32_e32 v32, v33, v31
	v_fma_f32 v29, -v29, v32, v30
	v_div_fmas_f32 v29, v29, v31, v32
	v_div_fixup_f32 v86, v29, v28, 1.0
	v_pk_mul_f32 v[28:29], v[64:65], v[86:87] op_sel_hi:[1,0]
	v_pk_mul_f32 v[30:31], v[62:63], v[86:87] op_sel_hi:[1,0]
	v_pk_mul_f32 v[32:33], v[68:69], v[86:87] op_sel_hi:[1,0]
	v_pk_mul_f32 v[34:35], v[66:67], v[86:87] op_sel_hi:[1,0]
	v_pk_mul_f32 v[30:31], v[40:41], v[30:31]
	v_pk_mul_f32 v[28:29], v[42:43], v[28:29]
	v_pk_mul_f32 v[34:35], v[36:37], v[34:35]
	v_pk_mul_f32 v[32:33], v[38:39], v[32:33]
	v_pk_fma_f32 v[28:29], v[54:55], v[28:29], v[50:51]
	v_pk_fma_f32 v[36:37], v[52:53], v[30:31], v[48:49]
	v_pk_fma_f32 v[30:31], v[58:59], v[32:33], v[46:47]
	v_pk_fma_f32 v[32:33], v[56:57], v[34:35], v[44:45]
	v_cvt_pk_bf16_f32 v31, v30, v31
	v_cvt_pk_bf16_f32 v30, v32, v33
	v_cvt_pk_bf16_f32 v29, v28, v29
	v_cvt_pk_bf16_f32 v28, v36, v37
	global_store_dwordx4 v[60:61], v[28:31], off
	s_nop 1
	s_waitcnt vmcnt(13)
	v_mov_b32_e32 v28, v192
	v_mov_b32_e32 v29, v193
	v_mov_b32_e32 v30, v194
	v_mov_b32_e32 v31, v195
	s_nop 0
	v_mov_b32_e32 v32, v196
	v_mov_b32_e32 v33, v197
	v_mov_b32_e32 v34, v198
	v_mov_b32_e32 v35, v199
	v_mov_b32_e32 v36, v200
	v_mov_b32_e32 v37, v201
	v_mov_b32_e32 v38, v202
	v_mov_b32_e32 v39, v203
	v_mov_b32_e32 v40, v204
	v_mov_b32_e32 v41, v205
	v_mov_b32_e32 v42, v206
	v_mov_b32_e32 v43, v207
	v_mov_b32_e32 v44, v208
	v_mov_b32_e32 v45, v209
	v_mov_b32_e32 v46, v210
	v_mov_b32_e32 v47, v211
	v_mov_b32_e32 v48, v212
	v_mov_b32_e32 v49, v213
	v_mov_b32_e32 v50, v214
	v_mov_b32_e32 v51, v215
	v_mov_b32_e32 v54, v73
	v_mov_b32_e32 v55, v75
	v_mov_b32_e32 v73, v74
	v_pk_mul_f32 v[54:55], v[54:55], v[86:87] op_sel_hi:[1,0]
	v_pk_mul_f32 v[56:57], v[72:73], v[86:87] op_sel_hi:[1,0]
	v_pk_mul_f32 v[58:59], v[76:77], v[86:87] op_sel_hi:[1,0]
	v_pk_mul_f32 v[60:61], v[70:71], v[86:87] op_sel_hi:[1,0]
	v_add_co_u32_e32 v52, vcc, s6, v12
	v_pk_mul_f32 v[16:17], v[16:17], v[86:87] op_sel_hi:[1,0]
	s_nop 0
	v_addc_co_u32_e32 v53, vcc, -1, v13, vcc
	v_pk_mul_f32 v[6:7], v[6:7], v[86:87] op_sel_hi:[1,0]
	v_pk_mul_f32 v[14:15], v[14:15], v[86:87] op_sel_hi:[1,0]
	v_pk_mul_f32 v[4:5], v[4:5], v[86:87] op_sel_hi:[1,0]
	v_lshl_add_u64 v[12:13], v[12:13], 0, s[70:71]
	s_nop 0
	v_pk_mul_f32 v[28:29], v[28:29], v[56:57]
	v_pk_mul_f32 v[30:31], v[30:31], v[54:55]
	s_nop 0
	v_pk_add_f32 v[34:35], v[34:35], 1.0 op_sel_hi:[1,0]
	v_pk_add_f32 v[32:33], v[32:33], 1.0 op_sel_hi:[1,0]
	s_nop 0
	v_pk_mul_f32 v[36:37], v[36:37], v[60:61]
	v_pk_mul_f32 v[38:39], v[38:39], v[58:59]
	s_nop 0
	v_pk_add_f32 v[42:43], v[42:43], 1.0 op_sel_hi:[1,0]
	v_pk_add_f32 v[40:41], v[40:41], 1.0 op_sel_hi:[1,0]
	s_nop 0
	v_pk_fma_f32 v[34:35], v[34:35], v[30:31], v[46:47]
	v_pk_fma_f32 v[28:29], v[32:33], v[28:29], v[44:45]
	s_nop 0
	v_pk_fma_f32 v[32:33], v[42:43], v[38:39], v[50:51]
	v_pk_fma_f32 v[30:31], v[40:41], v[36:37], v[48:49]
	v_cvt_pk_bf16_f32 v28, v28, v29
	v_cvt_pk_bf16_f32 v30, v30, v31
	v_cvt_pk_bf16_f32 v31, v32, v33
	v_cvt_pk_bf16_f32 v29, v34, v35
	global_store_dwordx4 v[52:53], v[28:31], off offset:-3072
	s_nop 1
	s_waitcnt vmcnt(8)
; __device__ __forceinline__ void phase_u_h(const Params& p, int l, int wave, int lane, int G) {
;     ...
;         for (int j = 0; j < 4; ++j) { const int col = 8 * lane + 512 * j;
;             h8 o;
; #pragma unroll
;             for (int hh = 0; hh < 2; ++hh) { const int c = col + 4 * hh;
;                 const f32x4 nw = *(const f32x4*)(p.norm_w + l * DM + c), sh = *(const f32x4*)(mb + c), sc = *(const f32x4*)(mb + 2048 + c);
;                 const f32x4 uu = (v[2 * j + hh] * rinv) * nw * (sc + 1.f) + sh;
;                 o[4 * hh] = op16(uu[0], INPROJ_BF16); o[4 * hh + 1] = op16(uu[1], INPROJ_BF16); o[4 * hh + 2] = op16(uu[2], INPROJ_BF16); o[4 * hh + 3] = op16(uu[3], INPROJ_BF16); }
;             *(h8*)(U + (size_t)row * DM + col) = o; }
	v_mov_b32_e32 v28, v216
	v_mov_b32_e32 v29, v217
	v_mov_b32_e32 v30, v218
	v_mov_b32_e32 v31, v219
	s_nop 0
	v_mov_b32_e32 v32, v220
	v_mov_b32_e32 v33, v221
	v_mov_b32_e32 v34, v222
	v_mov_b32_e32 v35, v223
	v_mov_b32_e32 v36, v224
	v_mov_b32_e32 v37, v225
	v_mov_b32_e32 v38, v226
	v_mov_b32_e32 v39, v227
	v_mov_b32_e32 v40, v228
	v_mov_b32_e32 v41, v229
	v_mov_b32_e32 v42, v230
	v_mov_b32_e32 v43, v231
	v_mov_b32_e32 v44, v232
	v_mov_b32_e32 v45, v233
	v_mov_b32_e32 v46, v234
	v_mov_b32_e32 v47, v235
	v_mov_b32_e32 v48, v236
	v_mov_b32_e32 v49, v237
	v_mov_b32_e32 v50, v238
	v_mov_b32_e32 v51, v239
	v_mov_b32_e32 v54, v83
	v_mov_b32_e32 v55, v85
	v_mov_b32_e32 v83, v84
	v_pk_mul_f32 v[56:57], v[80:81], v[86:87] op_sel_hi:[1,0]
	v_pk_mul_f32 v[58:59], v[78:79], v[86:87] op_sel_hi:[1,0]
	v_pk_mul_f32 v[54:55], v[54:55], v[86:87] op_sel_hi:[1,0]
	v_pk_mul_f32 v[60:61], v[82:83], v[86:87] op_sel_hi:[1,0]
	s_nop 0
	v_pk_mul_f32 v[28:29], v[28:29], v[58:59]
	v_pk_mul_f32 v[30:31], v[30:31], v[56:57]
	s_nop 0
	v_pk_add_f32 v[34:35], v[34:35], 1.0 op_sel_hi:[1,0]
	v_pk_add_f32 v[32:33], v[32:33], 1.0 op_sel_hi:[1,0]
	s_nop 0
	v_pk_mul_f32 v[36:37], v[60:61], v[36:37]
	v_pk_mul_f32 v[38:39], v[54:55], v[38:39]
	s_nop 0
	v_pk_add_f32 v[42:43], v[42:43], 1.0 op_sel_hi:[1,0]
	v_pk_add_f32 v[40:41], v[40:41], 1.0 op_sel_hi:[1,0]
	s_nop 0
	v_pk_fma_f32 v[34:35], v[30:31], v[34:35], v[46:47]
	v_pk_fma_f32 v[28:29], v[28:29], v[32:33], v[44:45]
	s_nop 0
	v_pk_fma_f32 v[32:33], v[38:39], v[42:43], v[50:51]
	v_pk_fma_f32 v[30:31], v[36:37], v[40:41], v[48:49]
	v_cvt_pk_bf16_f32 v28, v28, v29
	v_cvt_pk_bf16_f32 v30, v30, v31
	v_cvt_pk_bf16_f32 v31, v32, v33
	v_cvt_pk_bf16_f32 v29, v34, v35
	global_store_dwordx4 v[52:53], v[28:31], off offset:-2048
	s_nop 1
	s_waitcnt vmcnt(3)
	v_mov_b32_e32 v28, v240
	v_mov_b32_e32 v29, v241
	v_mov_b32_e32 v30, v242
	v_mov_b32_e32 v31, v243
	s_nop 0
	v_mov_b32_e32 v32, v244
	v_mov_b32_e32 v33, v245
	v_mov_b32_e32 v34, v246
	v_mov_b32_e32 v35, v247
	v_mov_b32_e32 v36, v108
	v_mov_b32_e32 v37, v109
	v_mov_b32_e32 v38, v110
	v_mov_b32_e32 v39, v111
	v_mov_b32_e32 v40, v112
	v_mov_b32_e32 v41, v113
	v_mov_b32_e32 v42, v114
	v_mov_b32_e32 v43, v115
	v_mov_b32_e32 v44, v116
	v_mov_b32_e32 v45, v117
	v_mov_b32_e32 v46, v118
	v_mov_b32_e32 v47, v119
	v_mov_b32_e32 v48, v120
	v_mov_b32_e32 v49, v121
	v_mov_b32_e32 v50, v122
	v_mov_b32_e32 v51, v123
	s_nop 0
	v_pk_mul_f32 v[6:7], v[6:7], v[28:29]
	v_pk_mul_f32 v[16:17], v[16:17], v[30:31]
	s_nop 0
	v_pk_add_f32 v[28:29], v[34:35], 1.0 op_sel_hi:[1,0]
	v_pk_add_f32 v[30:31], v[32:33], 1.0 op_sel_hi:[1,0]
	s_nop 0
	v_pk_mul_f32 v[4:5], v[4:5], v[36:37]
	v_pk_mul_f32 v[14:15], v[14:15], v[38:39]
	s_nop 0
	v_pk_add_f32 v[32:33], v[42:43], 1.0 op_sel_hi:[1,0]
	v_pk_add_f32 v[34:35], v[40:41], 1.0 op_sel_hi:[1,0]
	s_nop 0
	v_pk_fma_f32 v[16:17], v[16:17], v[28:29], v[46:47]
	v_pk_fma_f32 v[28:29], v[6:7], v[30:31], v[44:45]
	s_nop 0
	v_pk_fma_f32 v[14:15], v[14:15], v[32:33], v[50:51]
	v_pk_fma_f32 v[4:5], v[4:5], v[34:35], v[48:49]
	v_cvt_pk_bf16_f32 v7, v14, v15
	v_cvt_pk_bf16_f32 v6, v4, v5
	v_cvt_pk_bf16_f32 v4, v28, v29
	v_cvt_pk_bf16_f32 v5, v16, v17
	global_store_dwordx4 v[52:53], v[4:7], off offset:-1024
	s_cbranch_scc1 .LBB0_232

; __device__ __forceinline__ float load_hrow(const half_t* hrow, int lane, f32x4 (&v)[8]) {
;     float ss = 0.f;
; #pragma unroll
;     for (int j = 0; j < 4; ++j) { const h8 x = *(const h8*)(hrow + 8 * lane + 512 * j);
;         v[2 * j] = (f32x4){(float)x[0], (float)x[1], (float)x[2], (float)x[3]}; v[2 * j + 1] = (f32x4){(float)x[4], (float)x[5], (float)x[6], (float)x[7]};
;         ss += (v[2 * j][0] * v[2 * j][0] + v[2 * j][1] * v[2 * j][1]) + (v[2 * j][2] * v[2 * j][2] + v[2 * j][3] * v[2 * j][3]);
;         ss += (v[2 * j + 1][0] * v[2 * j + 1][0] + v[2 * j + 1][1] * v[2 * j + 1][1]) + (v[2 * j + 1][2] * v[2 * j + 1][2] + v[2 * j + 1][3] * v[2 * j + 1][3]); }
; __device__ __forceinline__ void phase_final(const Params& p, int wave, int lane, int G) {
;     const half_t* Hh = (const half_t*)(p.ws + WS_H);
;     const int gw = blockIdx.x * 8 + wave, NGW = G * 8;
;     for (int row = gw; row < NTOK; row += NGW) {
;         f32x4 v[8];
;         const float ss = wave_sum(load_hrow(Hh + (size_t)row * DM, lane, v), lane);
;         const float rinv = 1.0f / sqrtf(ss * (1.f / DM) + EPS);
; #pragma unroll
;         for (int j = 0; j < 4; ++j)
; #pragma unroll
;             for (int hh = 0; hh < 2; ++hh) { const int c = 8 * lane + 512 * j + 4 * hh;
;                 const f32x4 nw = *(const f32x4*)(p.fnorm_w + c);
;                 *(f32x4*)(p.out + (size_t)row * DM + c) = (v[2 * j + hh] * rinv) * nw; }
;     }
.LBB0_730:
	v_readlane_b32 s1, v252, 11
	v_readfirstlane_b32 s0, v180
	s_ashr_i32 s0, s0, 6
	s_add_i32 s2, s0, s1
	s_cmpk_gt_i32 s2, 0x1fff
	s_cbranch_scc1 .LBB0_733
	s_ashr_i32 s3, s2, 31
	s_lshl_b64 s[0:1], s[2:3], 12
	v_and_b32_e32 v10, 63, v180
	v_mov_b32_e32 v13, 0
	s_add_u32 s0, s66, s0
	v_lshlrev_b32_e32 v0, 2, v10
	v_lshlrev_b32_e32 v12, 5, v10
	v_lshlrev_b32_e32 v10, 4, v10
	v_mov_b32_e32 v11, v13
	s_addc_u32 s1, s67, s1
	v_lshl_add_u64 v[10:11], s[0:1], 0, v[10:11]
	s_mov_b64 s[0:1], 0x2c230000
	v_readlane_b32 s4, v252, 0
	v_lshl_add_u64 v[10:11], v[10:11], 0, s[0:1]
	s_lshl_b64 s[0:1], s[2:3], 13
	v_readlane_b32 s6, v252, 2
	v_readlane_b32 s7, v252, 3
	v_readlane_b32 s10, v252, 6
	v_readlane_b32 s11, v252, 7
	s_add_u32 s0, s64, s0
	s_mov_b64 s[6:7], s[10:11]
	s_addc_u32 s1, s65, s1
	v_xor_b32_e32 v14, 4, v0
	v_xor_b32_e32 v15, 8, v0
	v_xor_b32_e32 v16, 16, v0
	v_xor_b32_e32 v17, 32, v0
	v_xor_b32_e32 v18, 64, v0
	v_xor_b32_e32 v19, 0x80, v0
	v_lshl_add_u64 v[0:1], s[6:7], 0, v[12:13]
	v_or_b32_e32 v2, 0x1000, v12
	v_mov_b32_e32 v3, v13
	v_or_b32_e32 v4, 0x1010, v12
	v_mov_b32_e32 v5, v13
	v_or_b32_e32 v6, 0x1800, v12
	v_mov_b32_e32 v7, v13
	v_or_b32_e32 v8, 0x1810, v12
	v_mov_b32_e32 v9, v13
	v_lshl_add_u64 v[12:13], s[0:1], 0, v[12:13]
	s_mov_b64 s[0:1], 0x1000
	v_lshl_add_u64 v[2:3], s[6:7], 0, v[2:3]
	v_lshl_add_u64 v[4:5], s[6:7], 0, v[4:5]
	v_lshl_add_u64 v[6:7], s[6:7], 0, v[6:7]
	v_lshl_add_u64 v[8:9], s[6:7], 0, v[8:9]
	v_lshl_add_u64 v[12:13], v[12:13], 0, s[0:1]
	v_mov_b32_e32 v20, 0x358637bd
	s_mov_b32 s3, 0xf800000
	v_mov_b32_e32 v21, 0x260
	v_readlane_b32 s5, v252, 1
	v_readlane_b32 s8, v252, 4
	v_readlane_b32 s9, v252, 5
	global_load_dwordx4 v[100:103], v[0:1], off
	global_load_dwordx4 v[104:107], v[0:1], off offset:16
	global_load_dwordx4 v[108:111], v[0:1], off offset:2048
	global_load_dwordx4 v[112:115], v[0:1], off offset:2064
	global_load_dwordx4 v[116:119], v[2:3], off
	global_load_dwordx4 v[120:123], v[4:5], off
	global_load_dwordx4 v[124:127], v[6:7], off
	global_load_dwordx4 v[128:131], v[8:9], off
.LBB0_732:
	global_load_dwordx4 v[22:25], v[10:11], off
	global_load_dwordx4 v[26:29], v[10:11], off offset:1024
	global_load_dwordx4 v[30:33], v[10:11], off offset:2048
	global_load_dwordx4 v[34:37], v[10:11], off offset:3072
	s_add_i32 s2, s2, s68
	v_lshl_add_u64 v[10:11], v[10:11], 0, s[70:71]
	s_cmpk_lt_i32 s2, 0x2000
	s_waitcnt vmcnt(3)
	v_cvt_f32_f16_sdwa v43, v22 dst_sel:DWORD dst_unused:UNUSED_PAD src0_sel:WORD_1
	v_cvt_f32_f16_sdwa v45, v23 dst_sel:DWORD dst_unused:UNUSED_PAD src0_sel:WORD_1
	v_cvt_f32_f16_sdwa v47, v24 dst_sel:DWORD dst_unused:UNUSED_PAD src0_sel:WORD_1
	v_cvt_f32_f16_sdwa v49, v25 dst_sel:DWORD dst_unused:UNUSED_PAD src0_sel:WORD_1
	v_cvt_f32_f16_e32 v42, v22
	v_cvt_f32_f16_e32 v44, v23
	v_cvt_f32_f16_e32 v46, v24
	v_cvt_f32_f16_e32 v48, v25
	s_waitcnt vmcnt(2)
	v_cvt_f32_f16_e32 v53, v27
	v_cvt_f32_f16_e32 v52, v26
	v_cvt_f32_f16_sdwa v27, v27 dst_sel:DWORD dst_unused:UNUSED_PAD src0_sel:WORD_1
	v_cvt_f32_f16_sdwa v26, v26 dst_sel:DWORD dst_unused:UNUSED_PAD src0_sel:WORD_1
	v_cvt_f32_f16_e32 v50, v28
	v_cvt_f32_f16_e32 v54, v29
	v_cvt_f32_f16_sdwa v51, v28 dst_sel:DWORD dst_unused:UNUSED_PAD src0_sel:WORD_1
	v_cvt_f32_f16_sdwa v55, v29 dst_sel:DWORD dst_unused:UNUSED_PAD src0_sel:WORD_1
	s_waitcnt vmcnt(1)
	v_cvt_f32_f16_sdwa v29, v30 dst_sel:DWORD dst_unused:UNUSED_PAD src0_sel:WORD_1
	v_cvt_f32_f16_e32 v28, v30
	v_cvt_f32_f16_sdwa v57, v31 dst_sel:DWORD dst_unused:UNUSED_PAD src0_sel:WORD_1
	v_cvt_f32_f16_e32 v56, v31
	v_mov_b32_e32 v24, v47
	v_mov_b32_e32 v25, v43
	v_mov_b32_e32 v64, v49
	v_mov_b32_e32 v65, v45
	s_waitcnt vmcnt(0)
	v_cvt_f32_f16_sdwa v59, v34 dst_sel:DWORD dst_unused:UNUSED_PAD src0_sel:WORD_1
	v_cvt_f32_f16_e32 v58, v34
	v_cvt_f32_f16_sdwa v61, v36 dst_sel:DWORD dst_unused:UNUSED_PAD src0_sel:WORD_1
	v_cvt_f32_f16_e32 v60, v36
	v_cvt_f32_f16_sdwa v63, v37 dst_sel:DWORD dst_unused:UNUSED_PAD src0_sel:WORD_1
	v_cvt_f32_f16_e32 v62, v37
	v_cvt_f32_f16_sdwa v37, v35 dst_sel:DWORD dst_unused:UNUSED_PAD src0_sel:WORD_1
	v_cvt_f32_f16_e32 v36, v35
	v_mov_b32_e32 v22, v46
	v_mov_b32_e32 v23, v42
	v_mov_b32_e32 v34, v48
	v_mov_b32_e32 v35, v44
	v_pk_mul_f32 v[24:25], v[24:25], v[24:25]
	v_pk_mul_f32 v[64:65], v[64:65], v[64:65]
	v_cvt_f32_f16_e32 v31, v33
	v_cvt_f32_f16_e32 v30, v32
	v_cvt_f32_f16_sdwa v33, v33 dst_sel:DWORD dst_unused:UNUSED_PAD src0_sel:WORD_1
	v_cvt_f32_f16_sdwa v32, v32 dst_sel:DWORD dst_unused:UNUSED_PAD src0_sel:WORD_1
	v_pk_mul_f32 v[66:67], v[26:27], v[26:27]
	v_pk_fma_f32 v[22:23], v[22:23], v[22:23], v[24:25]
	v_pk_fma_f32 v[24:25], v[34:35], v[34:35], v[64:65]
	v_mul_f32_e32 v68, v54, v54
	v_mul_f32_e32 v74, v50, v50
	v_pk_fma_f32 v[66:67], v[52:53], v[52:53], v[66:67]
	v_pk_add_f32 v[22:23], v[22:23], v[24:25]
	v_pk_mul_f32 v[70:71], v[28:29], v[28:29]
	v_pk_mul_f32 v[72:73], v[56:57], v[56:57]
	v_pk_fma_f32 v[68:69], v[54:55], v[54:55], v[68:69] op_sel_hi:[1,1,0]
	v_pk_fma_f32 v[74:75], v[50:51], v[50:51], v[74:75] op_sel_hi:[1,1,0]
	v_pk_add_f32 v[34:35], v[66:67], v[66:67] op_sel_hi:[0,1]
	v_pk_add_f32 v[22:23], v[22:23], v[22:23] op_sel_hi:[0,1]
	v_mov_b32_e32 v74, v70
	v_mov_b32_e32 v68, v71
	v_mov_b32_e32 v34, v73
	v_mov_b32_e32 v22, v72
	v_pk_mul_f32 v[76:77], v[32:33], v[32:33]
	v_pk_add_f32 v[24:25], v[74:75], v[68:69]
	v_pk_add_f32 v[22:23], v[22:23], v[34:35]
	v_mul_f32_e32 v78, v36, v36
	v_mul_f32_e32 v84, v58, v58
	v_pk_fma_f32 v[76:77], v[30:31], v[30:31], v[76:77]
	v_pk_add_f32 v[22:23], v[24:25], v[22:23]
	v_pk_mul_f32 v[80:81], v[60:61], v[60:61]
	v_pk_mul_f32 v[82:83], v[62:63], v[62:63]
	v_pk_fma_f32 v[78:79], v[36:37], v[36:37], v[78:79] op_sel_hi:[1,1,0]
	v_pk_fma_f32 v[84:85], v[58:59], v[58:59], v[84:85] op_sel_hi:[1,1,0]
	v_pk_add_f32 v[64:65], v[76:77], v[76:77] op_sel_hi:[0,1]
	v_pk_add_f32 v[22:23], v[22:23], v[22:23] op_sel_hi:[0,1]
	v_mov_b32_e32 v84, v80
	v_mov_b32_e32 v78, v81
	v_mov_b32_e32 v64, v82
	v_mov_b32_e32 v22, v83
	v_pk_add_f32 v[66:67], v[84:85], v[78:79]
	v_pk_add_f32 v[22:23], v[64:65], v[22:23]
	s_nop 0
	v_pk_add_f32 v[22:23], v[66:67], v[22:23]
	s_nop 0
	v_add_f32_e32 v22, v22, v23
	ds_bpermute_b32 v23, v14, v22
	s_waitcnt lgkmcnt(0)
; __device__ __forceinline__ float shx(float v, int lane, int m) { return __builtin_bit_cast(float, __builtin_amdgcn_ds_bpermute((lane ^ m) << 2, __builtin_bit_cast(int, v))); }
; __device__ __forceinline__ float wave_sum(float v, int lane) {
; #pragma unroll
;     for (int o = 1; o < 64; o <<= 1) v += shx(v, lane, o);
;     return v;
; __device__ __forceinline__ void phase_final(const Params& p, int wave, int lane, int G) {
;     ...
;     for (int row = gw; row < NTOK; row += NGW) {
;         f32x4 v[8];
;         const float ss = wave_sum(load_hrow(Hh + (size_t)row * DM, lane, v), lane);
;         const float rinv = 1.0f / sqrtf(ss * (1.f / DM) + EPS);
; #pragma unroll
;         for (int j = 0; j < 4; ++j)
; #pragma unroll
;             for (int hh = 0; hh < 2; ++hh) { const int c = 8 * lane + 512 * j + 4 * hh;
;                 const f32x4 nw = *(const f32x4*)(p.fnorm_w + c);
;                 *(f32x4*)(p.out + (size_t)row * DM + c) = (v[2 * j + hh] * rinv) * nw; }
;     }
	v_add_f32_e32 v22, v22, v23
	ds_bpermute_b32 v23, v15, v22
	s_waitcnt lgkmcnt(0)
	v_add_f32_e32 v22, v22, v23
	ds_bpermute_b32 v23, v16, v22
	s_waitcnt lgkmcnt(0)
	v_add_f32_e32 v22, v22, v23
	ds_bpermute_b32 v23, v17, v22
	s_waitcnt lgkmcnt(0)
	v_add_f32_e32 v22, v22, v23
	ds_bpermute_b32 v23, v18, v22
	s_waitcnt lgkmcnt(0)
	v_add_f32_e32 v22, v22, v23
	ds_bpermute_b32 v23, v19, v22
	s_waitcnt lgkmcnt(0)
	v_add_f32_e32 v22, v22, v23
	v_fmamk_f32 v22, v22, 0x3a000000, v20
	v_mul_f32_e32 v23, 0x4f800000, v22
	v_cmp_gt_f32_e32 vcc, s3, v22
	s_nop 1
	v_cndmask_b32_e32 v22, v22, v23, vcc
	v_sqrt_f32_e32 v23, v22
	s_nop 0
	v_add_u32_e32 v24, -1, v23
	v_add_u32_e32 v25, 1, v23
	v_fma_f32 v34, -v24, v23, v22
	v_fma_f32 v35, -v25, v23, v22
	v_cmp_ge_f32_e64 s[0:1], 0, v34
	s_nop 1
	v_cndmask_b32_e64 v23, v23, v24, s[0:1]
	v_cmp_lt_f32_e64 s[0:1], 0, v35
	s_nop 1
	v_cndmask_b32_e64 v23, v23, v25, s[0:1]
	v_mul_f32_e32 v24, 0x37800000, v23
	v_cndmask_b32_e32 v23, v23, v24, vcc
	v_cmp_class_f32_e32 vcc, v22, v21
	s_nop 1
	v_cndmask_b32_e32 v22, v23, v22, vcc
	v_div_scale_f32 v23, s[0:1], v22, v22, 1.0
	v_rcp_f32_e32 v25, v23
	v_div_scale_f32 v24, vcc, 1.0, v22, 1.0
	v_fma_f32 v34, -v23, v25, 1.0
	v_fmac_f32_e32 v25, v34, v25
	v_mul_f32_e32 v34, v24, v25
	v_fma_f32 v35, -v23, v34, v24
	v_fmac_f32_e32 v34, v35, v25
	v_fma_f32 v23, -v23, v34, v24
	v_div_fmas_f32 v23, v23, v25, v34
	v_div_fixup_f32 v34, v23, v22, 1.0
	v_pk_mul_f32 v[22:23], v[42:43], v[34:35] op_sel_hi:[1,0]
	v_pk_mul_f32 v[24:25], v[44:45], v[34:35] op_sel_hi:[1,0]
	v_mov_b32_e32 v38, v100
	v_mov_b32_e32 v39, v101
	v_mov_b32_e32 v40, v102
	v_mov_b32_e32 v41, v103
	v_pk_mul_f32 v[22:23], v[38:39], v[22:23]
	v_pk_mul_f32 v[24:25], v[40:41], v[24:25]
	global_store_dwordx4 v[12:13], v[22:25], off offset:-4096
	s_nop 1
	v_mov_b32_e32 v22, v104
	v_mov_b32_e32 v23, v105
	v_mov_b32_e32 v24, v106
	v_mov_b32_e32 v25, v107
	v_pk_mul_f32 v[38:39], v[48:49], v[34:35] op_sel_hi:[1,0]
	v_pk_mul_f32 v[40:41], v[46:47], v[34:35] op_sel_hi:[1,0]
	v_pk_mul_f32 v[28:29], v[28:29], v[34:35] op_sel_hi:[1,0]
	s_nop 0
	v_pk_mul_f32 v[22:23], v[22:23], v[40:41]
	v_pk_mul_f32 v[24:25], v[24:25], v[38:39]
	global_store_dwordx4 v[12:13], v[22:25], off offset:-4080
	s_nop 1
	v_mov_b32_e32 v22, v108
	v_mov_b32_e32 v23, v109
	v_mov_b32_e32 v24, v110
	v_mov_b32_e32 v25, v111
	v_mov_b32_e32 v38, v53
	v_mov_b32_e32 v39, v27
	v_mov_b32_e32 v53, v26
	v_pk_mul_f32 v[26:27], v[38:39], v[34:35] op_sel_hi:[1,0]
	v_pk_mul_f32 v[38:39], v[52:53], v[34:35] op_sel_hi:[1,0]
	s_nop 0
	v_pk_mul_f32 v[24:25], v[24:25], v[26:27]
	v_pk_mul_f32 v[22:23], v[22:23], v[38:39]
	global_store_dwordx4 v[12:13], v[22:25], off offset:-2048
	s_nop 1
	v_mov_b32_e32 v22, v112
	v_mov_b32_e32 v23, v113
	v_mov_b32_e32 v24, v114
	v_mov_b32_e32 v25, v115
	v_pk_mul_f32 v[26:27], v[54:55], v[34:35] op_sel_hi:[1,0]
	v_pk_mul_f32 v[38:39], v[50:51], v[34:35] op_sel_hi:[1,0]
	s_nop 0
	v_pk_mul_f32 v[24:25], v[24:25], v[26:27]
	v_pk_mul_f32 v[22:23], v[22:23], v[38:39]
	global_store_dwordx4 v[12:13], v[22:25], off offset:-2032
	s_nop 1
	v_mov_b32_e32 v22, v116
	v_mov_b32_e32 v23, v117
	v_mov_b32_e32 v24, v118
	v_mov_b32_e32 v25, v119
	v_pk_mul_f32 v[26:27], v[56:57], v[34:35] op_sel_hi:[1,0]
	s_nop 0
	v_pk_mul_f32 v[22:23], v[22:23], v[28:29]
	v_pk_mul_f32 v[24:25], v[24:25], v[26:27]
	global_store_dwordx4 v[12:13], v[22:25], off
	s_nop 1
	v_mov_b32_e32 v22, v120
	v_mov_b32_e32 v23, v121
	v_mov_b32_e32 v24, v122
	v_mov_b32_e32 v25, v123
	v_mov_b32_e32 v26, v31
	v_mov_b32_e32 v27, v33
	v_mov_b32_e32 v31, v32
	v_pk_mul_f32 v[26:27], v[26:27], v[34:35] op_sel_hi:[1,0]
	v_pk_mul_f32 v[28:29], v[30:31], v[34:35] op_sel_hi:[1,0]
	s_nop 0
	v_pk_mul_f32 v[24:25], v[24:25], v[26:27]
	v_pk_mul_f32 v[22:23], v[22:23], v[28:29]
	global_store_dwordx4 v[12:13], v[22:25], off offset:16
	s_nop 1
	v_mov_b32_e32 v22, v124
	v_mov_b32_e32 v23, v125
	v_mov_b32_e32 v24, v126
	v_mov_b32_e32 v25, v127
	v_pk_mul_f32 v[26:27], v[36:37], v[34:35] op_sel_hi:[1,0]
	v_pk_mul_f32 v[28:29], v[58:59], v[34:35] op_sel_hi:[1,0]
	s_nop 0
	v_pk_mul_f32 v[24:25], v[24:25], v[26:27]
	v_pk_mul_f32 v[22:23], v[22:23], v[28:29]
	global_store_dwordx4 v[12:13], v[22:25], off offset:2048
	s_nop 1
	v_mov_b32_e32 v22, v128
	v_mov_b32_e32 v23, v129
	v_mov_b32_e32 v24, v130
	v_mov_b32_e32 v25, v131
	v_pk_mul_f32 v[26:27], v[62:63], v[34:35] op_sel_hi:[1,0]
	v_pk_mul_f32 v[28:29], v[60:61], v[34:35] op_sel_hi:[1,0]
	s_nop 0
	v_pk_mul_f32 v[24:25], v[24:25], v[26:27]
	v_pk_mul_f32 v[22:23], v[22:23], v[28:29]
	global_store_dwordx4 v[12:13], v[22:25], off offset:2064
	v_lshl_add_u64 v[12:13], v[12:13], 0, s[72:73]
	s_cbranch_scc1 .LBB0_732
